# attention tile loop: prefetch V fragments before softmax, max3 trees
# speedup vs baseline: 1.2059x; 1.2059x over previous
; #define LAS __attribute__((address_space(3)))
; DEV void attn_tile(LAS unsigned char* lds, const bf16x8 (&qf)[2][2], int tl, int kpos0, int mode, bool near, bool rowsel, const float (&cbias)[2],
;                    unsigned kb, unsigned vb_, unsigned btb, int g4, float (&mrun)[2], float (&lrun)[2], f32x4 (&O)[2][4]) {
;     f32x4 sc[2][4];
;     float ci[2];
; #pragma unroll
;     for (int hh = 0; hh < 2; ++hh) { const float mne = mrun[hh] < -1e29f ? 0.f : mrun[hh];
;         ci[hh] = near ? -mne : (((mode == 1 && !rowsel) ? NEG_ : cbias[hh]) - mne); }
;     {
;         bf16x8 kf[4][2];
; #pragma unroll
;         for (int kt = 0; kt < 4; ++kt) { kf[kt][0] = *(const LAS bf16x8*)(lds + kb + kt * 2304); kf[kt][1] = *(const LAS bf16x8*)(lds + kb + kt * 2304 + 64); }
;         __builtin_amdgcn_sched_barrier(0);
; #pragma unroll
;         for (int kt = 0; kt < 4; ++kt)
; #pragma unroll
;             for (int hh = 0; hh < 2; ++hh) sc[hh][kt] = __builtin_amdgcn_mfma_f32_16x16x32_bf16(kf[kt][0], qf[hh][0], (f32x4){ci[hh], ci[hh], ci[hh], ci[hh]}, 0, 0, 0);
; #pragma unroll
;         for (int kt = 0; kt < 4; ++kt)
; #pragma unroll
;             for (int hh = 0; hh < 2; ++hh) sc[hh][kt] = __builtin_amdgcn_mfma_f32_16x16x32_bf16(kf[kt][1], qf[hh][1], sc[hh][kt], 0, 0, 0);
;     }
;     ...
;     for (int dt = 0; dt < 4; ++dt)
; #pragma unroll
;         for (int kc = 0; kc < 2; ++kc) {
;             const u32x2 va = *(const LAS u32x2*)(lds + vb_ + dt * 2304 + kc * 64);
;             const u32x2 vb = *(const LAS u32x2*)(lds + vb_ + dt * 2304 + kc * 64 + 32);
;             const bf16x8 vf = as_bf16x8((u32x4){va.x, va.y, vb.x, vb.y});
.LBB0_269:
	s_cmp_ge_i32 s50, s36
	s_cselect_b64 s[4:5], -1, 0
	s_cmp_eq_u32 s97, 2
	s_cselect_b64 s[6:7], -1, 0
	s_cmp_eq_u32 s50, s17
	s_cselect_b64 s[42:43], -1, 0
	s_and_b64 s[6:7], s[6:7], s[42:43]
	s_or_b64 s[4:5], s[4:5], s[6:7]
	v_lshrrev_b32_e32 v64, s50, v127
	v_and_b32_e32 v64, 1, v64
	s_cmp_lg_u32 s97, 1
	v_cmp_eq_u32_e64 s[48:49], 1, v64
	s_cselect_b64 s[6:7], -1, 0
	s_or_b64 vcc, s[6:7], s[48:49]
	v_cmp_gt_f32_e64 s[44:45], s65, v149
	v_cndmask_b32_e32 v65, v223, v136, vcc
	v_cmp_gt_f32_e64 s[42:43], s65, v150
	v_cndmask_b32_e64 v64, v149, 0, s[44:45]
	v_sub_f32_e32 v65, v65, v64
	v_cndmask_b32_e64 v64, v65, -v64, s[4:5]
	v_cndmask_b32_e64 v65, v150, 0, s[42:43]
	v_cndmask_b32_e32 v66, v223, v137, vcc
	v_sub_f32_e32 v66, v66, v65
	v_cndmask_b32_e64 v68, v66, -v65, s[4:5]
	v_add_u32_e32 v65, v141, v152
	ds_read_b128 v[72:75], v65
	ds_read_b128 v[76:79], v65 offset:64
	ds_read_b128 v[80:83], v65 offset:2304
	ds_read_b128 v[84:87], v65 offset:2368
	ds_read_b128 v[88:91], v65 offset:4608
	ds_read_b128 v[154:157], v65 offset:4672
	ds_read_b128 v[92:95], v65 offset:6912
	ds_read_b128 v[158:161], v65 offset:6976
	v_mov_b32_e32 v65, v64
	v_mov_b32_e32 v66, v64
	v_mov_b32_e32 v67, v64
	v_mov_b32_e32 v69, v68
	v_mov_b32_e32 v70, v68
	v_mov_b32_e32 v71, v68
	s_waitcnt lgkmcnt(7)
	v_mfma_f32_16x16x32_bf16 v[162:165], v[72:75], v[8:11], v[64:67]
	s_mov_b64 s[6:7], -1
	s_and_b64 vcc, exec, s[4:5]
	v_mfma_f32_16x16x32_bf16 v[72:75], v[72:75], v[16:19], v[68:71]
	v_add_u32_e32 v228, v145, v152
	v_add_u32_e32 v229, 0x800, v228
	v_add_u32_e32 v230, 0x1000, v228
	v_add_u32_e32 v231, 0x1800, v228
	ds_read2_b64 v[232:235], v228 offset1:4
	ds_read2_b64 v[236:239], v228 offset0:8 offset1:12
	ds_read2_b64 v[240:243], v229 offset0:32 offset1:36
	ds_read2_b64 v[244:247], v229 offset0:40 offset1:44
	ds_read2_b64 v[248:251], v230 offset0:64 offset1:68
	ds_read2_b64 v[198:201], v230 offset0:72 offset1:76
	ds_read2_b64 v[202:205], v231 offset0:96 offset1:100
	ds_read2_b64 v[206:209], v231 offset0:104 offset1:108
	s_waitcnt lgkmcnt(13)
	v_mfma_f32_16x16x32_bf16 v[166:169], v[80:83], v[8:11], v[64:67]
	v_mfma_f32_16x16x32_bf16 v[80:83], v[80:83], v[16:19], v[68:71]
	s_waitcnt lgkmcnt(11)
	v_mfma_f32_16x16x32_bf16 v[180:183], v[88:91], v[8:11], v[64:67]
	v_mfma_f32_16x16x32_bf16 v[184:187], v[88:91], v[16:19], v[68:71]
	s_waitcnt lgkmcnt(9)
	v_mfma_f32_16x16x32_bf16 v[188:191], v[92:95], v[8:11], v[64:67]
	v_mfma_f32_16x16x32_bf16 v[68:71], v[92:95], v[16:19], v[68:71]
	v_mfma_f32_16x16x32_bf16 v[92:95], v[76:79], v[12:15], v[162:165]
	v_mfma_f32_16x16x32_bf16 v[76:79], v[76:79], v[20:23], v[72:75]
	v_mfma_f32_16x16x32_bf16 v[88:91], v[84:87], v[12:15], v[166:169]
	v_mfma_f32_16x16x32_bf16 v[72:75], v[84:87], v[20:23], v[80:83]
	v_mfma_f32_16x16x32_bf16 v[84:87], v[154:157], v[12:15], v[180:183]
	v_mfma_f32_16x16x32_bf16 v[64:67], v[154:157], v[20:23], v[184:187]
	s_waitcnt lgkmcnt(8)
	v_mfma_f32_16x16x32_bf16 v[80:83], v[158:161], v[12:15], v[188:191]
	v_mfma_f32_16x16x32_bf16 v[68:71], v[158:161], v[20:23], v[68:71]
	s_cbranch_vccnz .LBB0_271
	s_mov_b64 s[6:7], 0

; DEV void attn_tile(LAS unsigned char* lds, const bf16x8 (&qf)[2][2], int tl, int kpos0, int mode, bool near, bool rowsel, const float (&cbias)[2],
;                    unsigned kb, unsigned vb_, unsigned btb, int g4, float (&mrun)[2], float (&lrun)[2], f32x4 (&O)[2][4]) {
;     ...
;     bf16x8 pf[2][2];
; #pragma unroll
;     for (int hh = 0; hh < 2; ++hh) {
;         float lm = fmaxf(fmaxf(sc[hh][0][0], sc[hh][0][1]), fmaxf(sc[hh][0][2], sc[hh][0][3]));
; #pragma unroll
;         for (int kt = 1; kt < 4; ++kt) lm = fmaxf(lm, fmaxf(fmaxf(sc[hh][kt][0], sc[hh][kt][1]), fmaxf(sc[hh][kt][2], sc[hh][kt][3])));
;         const bool inval = mrun[hh] < -1e29f;
;         if (__any(lm > (inval ? -1e29f : 20.f))) {
;             float mx = fmaxf(lm, __shfl_xor(lm, 16)); mx = fmaxf(mx, __shfl_xor(mx, 32));
;             float d = 0.f, alpha = 1.f;
;             if (mx > -1e29f) { d = inval ? mx : fmaxf(mx, 0.f); alpha = inval ? 1.f : __builtin_amdgcn_exp2f(-d); mrun[hh] = inval ? mx : mrun[hh] + d; }
; #pragma unroll
;             for (int kt = 0; kt < 4; ++kt) sc[hh][kt] = sc[hh][kt] - d;
;             lrun[hh] *= alpha;
; #pragma unroll
;             for (int dt = 0; dt < 4; ++dt) O[hh][dt] = O[hh][dt] * alpha;
;         }
.LBB0_273:
	v_max3_f32 v153, v92, v93, v94
	v_max3_f32 v154, v95, v88, v89
	v_max3_f32 v155, v90, v91, v84
	v_max3_f32 v156, v85, v86, v87
	v_max3_f32 v157, v80, v81, v82
	v_max3_f32 v153, v153, v154, v155
	v_max3_f32 v156, v156, v157, v83
	v_max_f32_e32 v153, v153, v156
	v_cndmask_b32_e64 v154, v224, v225, s[44:45]
	v_cmp_gt_f32_e32 vcc, v153, v154
	s_cbranch_vccz .LBB0_275
	ds_bpermute_b32 v154, v143, v153
	v_max_f32_e32 v153, v153, v153
	s_waitcnt lgkmcnt(0)
	v_max_f32_e32 v154, v154, v154
	v_max_f32_e32 v153, v153, v154
	ds_bpermute_b32 v154, v144, v153
	s_waitcnt lgkmcnt(0)
	v_max_f32_e32 v154, v154, v154
	v_max_f32_e32 v153, v153, v154
	v_max_f32_e32 v154, 0, v153
	v_add_f32_e32 v155, v149, v154
	v_cndmask_b32_e64 v154, v154, v153, s[44:45]
	v_exp_f32_e64 v156, -v154
	v_cmp_lt_f32_e32 vcc, s65, v153
	v_cndmask_b32_e64 v155, v155, v153, s[44:45]
	s_nop 0
	v_cndmask_b32_e32 v153, 0, v154, vcc
	v_cndmask_b32_e64 v154, v156, 1.0, s[44:45]
	v_cndmask_b32_e32 v154, 1.0, v154, vcc
	v_cndmask_b32_e32 v149, v149, v155, vcc
	v_sub_f32_e32 v92, v92, v153
	v_sub_f32_e32 v93, v93, v153
	v_sub_f32_e32 v94, v94, v153
	v_sub_f32_e32 v95, v95, v153
	v_sub_f32_e32 v88, v88, v153
	v_sub_f32_e32 v89, v89, v153
	v_sub_f32_e32 v90, v90, v153
	v_sub_f32_e32 v91, v91, v153
	v_sub_f32_e32 v84, v84, v153
	v_sub_f32_e32 v85, v85, v153
	v_sub_f32_e32 v86, v86, v153
	v_sub_f32_e32 v87, v87, v153
	v_sub_f32_e32 v80, v80, v153
	v_sub_f32_e32 v81, v81, v153
	v_sub_f32_e32 v82, v82, v153
	v_sub_f32_e32 v83, v83, v153
	v_mul_f32_e32 v151, v151, v154
	v_pk_mul_f32 v[46:47], v[46:47], v[154:155] op_sel_hi:[1,0]
	v_pk_mul_f32 v[44:45], v[44:45], v[154:155] op_sel_hi:[1,0]
	v_pk_mul_f32 v[58:59], v[58:59], v[154:155] op_sel_hi:[1,0]
	v_pk_mul_f32 v[56:57], v[56:57], v[154:155] op_sel_hi:[1,0]
	v_pk_mul_f32 v[54:55], v[54:55], v[154:155] op_sel_hi:[1,0]
	v_pk_mul_f32 v[52:53], v[52:53], v[154:155] op_sel_hi:[1,0]
	v_pk_mul_f32 v[62:63], v[62:63], v[154:155] op_sel_hi:[1,0]
	v_pk_mul_f32 v[60:61], v[60:61], v[154:155] op_sel_hi:[1,0]
.LBB0_275:
	v_max3_f32 v161, v76, v77, v78
	v_max3_f32 v162, v79, v72, v73
	v_max3_f32 v163, v74, v75, v64
	v_max3_f32 v164, v65, v66, v67
	v_max3_f32 v165, v68, v69, v70
	v_exp_f32_e32 v92, v92
	v_exp_f32_e32 v93, v93
	v_exp_f32_e32 v94, v94
	v_exp_f32_e32 v95, v95
	v_exp_f32_e32 v88, v88
	v_exp_f32_e32 v89, v89
	v_exp_f32_e32 v90, v90
	v_exp_f32_e32 v91, v91
	v_exp_f32_e32 v153, v84
	v_exp_f32_e32 v154, v85
	v_exp_f32_e32 v155, v86
	v_exp_f32_e32 v156, v87
	v_exp_f32_e32 v157, v80
	v_exp_f32_e32 v158, v81
	v_exp_f32_e32 v159, v82
	v_exp_f32_e32 v160, v83
	v_max3_f32 v161, v161, v162, v163
	v_max3_f32 v164, v164, v165, v71
	v_max_f32_e32 v161, v161, v164
	v_cndmask_b32_e64 v162, v224, v225, s[42:43]
	v_cmp_gt_f32_e32 vcc, v161, v162
	v_cvt_pk_bf16_f32 v84, v92, v93
	v_cvt_pk_bf16_f32 v85, v94, v95
	v_cvt_pk_bf16_f32 v86, v88, v89
	v_cvt_pk_bf16_f32 v87, v90, v91
	v_cvt_pk_bf16_f32 v80, v153, v154
	v_cvt_pk_bf16_f32 v81, v155, v156
	v_cvt_pk_bf16_f32 v82, v157, v158
	v_cvt_pk_bf16_f32 v83, v159, v160
	s_cbranch_vccz .LBB0_277
	ds_bpermute_b32 v162, v143, v161
	v_max_f32_e32 v161, v161, v161
	s_waitcnt lgkmcnt(0)
	v_max_f32_e32 v162, v162, v162
	v_max_f32_e32 v161, v161, v162
	ds_bpermute_b32 v162, v144, v161
	s_waitcnt lgkmcnt(0)
	v_max_f32_e32 v162, v162, v162
	v_max_f32_e32 v161, v161, v162
	v_max_f32_e32 v162, 0, v161
	v_add_f32_e32 v163, v150, v162
	v_cndmask_b32_e64 v162, v162, v161, s[42:43]
	v_exp_f32_e64 v164, -v162
	v_cmp_lt_f32_e32 vcc, s65, v161
	v_cndmask_b32_e64 v163, v163, v161, s[42:43]
	s_nop 0
	v_cndmask_b32_e32 v161, 0, v162, vcc
	v_cndmask_b32_e64 v162, v164, 1.0, s[42:43]
	v_cndmask_b32_e32 v162, 1.0, v162, vcc
	v_cndmask_b32_e32 v150, v150, v163, vcc
	v_sub_f32_e32 v76, v76, v161
	v_sub_f32_e32 v77, v77, v161
	v_sub_f32_e32 v78, v78, v161
	v_sub_f32_e32 v79, v79, v161
	v_sub_f32_e32 v72, v72, v161
	v_sub_f32_e32 v73, v73, v161
	v_sub_f32_e32 v74, v74, v161
	v_sub_f32_e32 v75, v75, v161
	v_sub_f32_e32 v64, v64, v161
	v_sub_f32_e32 v65, v65, v161
	v_sub_f32_e32 v66, v66, v161
	v_sub_f32_e32 v67, v67, v161
	v_sub_f32_e32 v68, v68, v161
	v_sub_f32_e32 v69, v69, v161
	v_sub_f32_e32 v70, v70, v161
	v_sub_f32_e32 v71, v71, v161
	v_mul_f32_e32 v148, v148, v162
	v_pk_mul_f32 v[34:35], v[34:35], v[162:163] op_sel_hi:[1,0]
	v_pk_mul_f32 v[32:33], v[32:33], v[162:163] op_sel_hi:[1,0]
	v_pk_mul_f32 v[42:43], v[42:43], v[162:163] op_sel_hi:[1,0]
	v_pk_mul_f32 v[40:41], v[40:41], v[162:163] op_sel_hi:[1,0]
	v_pk_mul_f32 v[38:39], v[38:39], v[162:163] op_sel_hi:[1,0]
	v_pk_mul_f32 v[36:37], v[36:37], v[162:163] op_sel_hi:[1,0]
	v_pk_mul_f32 v[50:51], v[50:51], v[162:163] op_sel_hi:[1,0]
	v_pk_mul_f32 v[48:49], v[48:49], v[162:163] op_sel_hi:[1,0]
; #define LAS __attribute__((address_space(3)))
; DEV unsigned cvt_pk_bf16(float lo, float hi) { unsigned r; asm volatile("v_cvt_pk_bf16_f32 %0, %1, %2" : "=v"(r) : "v"(lo), "v"(hi)); return r; }
; DEV void attn_tile(LAS unsigned char* lds, const bf16x8 (&qf)[2][2], int tl, int kpos0, int mode, bool near, bool rowsel, const float (&cbias)[2],
;                    unsigned kb, unsigned vb_, unsigned btb, int g4, float (&mrun)[2], float (&lrun)[2], f32x4 (&O)[2][4]) {
;     ...
;         float rs = 0.f;
; #pragma unroll
;         for (int kt = 0; kt < 4; ++kt)
; #pragma unroll
;             for (int r = 0; r < 4; ++r) { const float p = __builtin_amdgcn_exp2f(sc[hh][kt][r]); sc[hh][kt][r] = p; rs += p; }
;         lrun[hh] += rs;
; #pragma unroll
;         for (int kc = 0; kc < 2; ++kc) { u32x4 w; w.x = cvt_pk_bf16(sc[hh][2 * kc][0], sc[hh][2 * kc][1]); w.y = cvt_pk_bf16(sc[hh][2 * kc][2], sc[hh][2 * kc][3]);
;             w.z = cvt_pk_bf16(sc[hh][2 * kc + 1][0], sc[hh][2 * kc + 1][1]); w.w = cvt_pk_bf16(sc[hh][2 * kc + 1][2], sc[hh][2 * kc + 1][3]); pf[hh][kc] = as_bf16x8(w); }
;     }
; #pragma unroll
;     for (int dt = 0; dt < 4; ++dt)
; #pragma unroll
;         for (int kc = 0; kc < 2; ++kc) {
;             const u32x2 va = *(const LAS u32x2*)(lds + vb_ + dt * 2304 + kc * 64);
;             const u32x2 vb = *(const LAS u32x2*)(lds + vb_ + dt * 2304 + kc * 64 + 32);
;             const bf16x8 vf = as_bf16x8((u32x4){va.x, va.y, vb.x, vb.y});
; #pragma unroll
;             for (int hh = 0; hh < 2; ++hh) O[hh][dt] = __builtin_amdgcn_mfma_f32_16x16x32_bf16(vf, pf[hh][kc], O[hh][dt], 0, 0, 0);
;         }
; }
; DEV void attn_item(LAS unsigned char* lds, const bf16_t* P, const bf16_t* QB, const bf16_t* KV, const bf16_t* KC, const bf16_t* VC, const float* rel_bias, bf16_t* OB, int b, int g, int qt) {
;     ...
;             if (mode_n != mode || !more) {
; #pragma unroll
;                 for (int hh = 0; hh < 2; ++hh) { float lt = lrun[hh]; lt += __shfl_xor(lt, 16); lt += __shfl_xor(lt, 32); const float sc = lt > 0.f ? gate[mode][hh] / lt : 0.f;
.LBB0_277:
	v_add_f32_e32 v92, 0, v92
	v_add_f32_e32 v92, v93, v92
	v_add_f32_e32 v92, v94, v92
	v_add_f32_e32 v92, v95, v92
	v_add_f32_e32 v88, v88, v92
	v_add_f32_e32 v88, v89, v88
	v_add_f32_e32 v88, v90, v88
	v_add_f32_e32 v88, v91, v88
	v_add_f32_e32 v88, v153, v88
	v_add_f32_e32 v88, v154, v88
	v_add_f32_e32 v88, v155, v88
	v_add_f32_e32 v88, v156, v88
	v_add_f32_e32 v88, v157, v88
	v_exp_f32_e32 v76, v76
	v_add_f32_e32 v88, v158, v88
	v_exp_f32_e32 v77, v77
	v_add_f32_e32 v88, v159, v88
	v_exp_f32_e32 v78, v78
	v_add_f32_e32 v88, v160, v88
	v_exp_f32_e32 v79, v79
	v_add_f32_e32 v151, v151, v88
	v_add_f32_e32 v88, 0, v76
	v_exp_f32_e32 v72, v72
	v_add_f32_e32 v88, v77, v88
	v_exp_f32_e32 v73, v73
	v_add_f32_e32 v88, v78, v88
	v_exp_f32_e32 v74, v74
	v_add_f32_e32 v88, v79, v88
	v_exp_f32_e32 v75, v75
	v_add_f32_e32 v88, v72, v88
	v_exp_f32_e32 v64, v64
	v_add_f32_e32 v88, v73, v88
	v_exp_f32_e32 v65, v65
	v_add_f32_e32 v88, v74, v88
	v_exp_f32_e32 v66, v66
	v_add_f32_e32 v88, v75, v88
	v_exp_f32_e32 v67, v67
	v_add_f32_e32 v88, v64, v88
	v_exp_f32_e32 v89, v68
	v_add_f32_e32 v88, v65, v88
	v_add_f32_e32 v88, v66, v88
	v_add_f32_e32 v88, v67, v88
	v_add_f32_e32 v68, v89, v88
	v_exp_f32_e32 v88, v69
	v_exp_f32_e32 v90, v70
	v_exp_f32_e32 v91, v71
	s_cmp_eq_u32 s96, s97
	v_add_f32_e32 v68, v88, v68
	v_add_f32_e32 v68, v90, v68
	v_add_f32_e32 v68, v91, v68
	v_add_f32_e32 v148, v148, v68
	v_cvt_pk_bf16_f32 v68, v76, v77
	v_cvt_pk_bf16_f32 v69, v78, v79
	v_cvt_pk_bf16_f32 v70, v72, v73
	v_cvt_pk_bf16_f32 v71, v74, v75
	v_cvt_pk_bf16_f32 v64, v64, v65
	v_cvt_pk_bf16_f32 v65, v66, v67
	v_cvt_pk_bf16_f32 v66, v89, v88
	v_cvt_pk_bf16_f32 v67, v90, v91
	s_waitcnt lgkmcnt(7)
	v_mfma_f32_16x16x32_bf16 v[44:47], v[232:235], v[84:87], v[44:47]
	s_cselect_b64 s[4:5], -1, 0
	s_and_b64 s[4:5], s[4:5], s[54:55]
	v_mfma_f32_16x16x32_bf16 v[32:35], v[232:235], v[68:71], v[32:35]
	s_and_b64 vcc, exec, s[4:5]
	s_waitcnt lgkmcnt(6)
	v_mfma_f32_16x16x32_bf16 v[44:47], v[236:239], v[80:83], v[44:47]
	v_mfma_f32_16x16x32_bf16 v[32:35], v[236:239], v[64:67], v[32:35]
	s_waitcnt lgkmcnt(5)
	v_mfma_f32_16x16x32_bf16 v[56:59], v[240:243], v[84:87], v[56:59]
	v_mfma_f32_16x16x32_bf16 v[40:43], v[240:243], v[68:71], v[40:43]
	s_waitcnt lgkmcnt(4)
	v_mfma_f32_16x16x32_bf16 v[56:59], v[244:247], v[80:83], v[56:59]
	v_mfma_f32_16x16x32_bf16 v[40:43], v[244:247], v[64:67], v[40:43]
	s_waitcnt lgkmcnt(3)
	v_mfma_f32_16x16x32_bf16 v[52:55], v[248:251], v[84:87], v[52:55]
	v_mfma_f32_16x16x32_bf16 v[36:39], v[248:251], v[68:71], v[36:39]
	s_waitcnt lgkmcnt(2)
	v_mfma_f32_16x16x32_bf16 v[52:55], v[198:201], v[80:83], v[52:55]
	v_mfma_f32_16x16x32_bf16 v[36:39], v[198:201], v[64:67], v[36:39]
	s_waitcnt lgkmcnt(1)
	v_mfma_f32_16x16x32_bf16 v[48:51], v[202:205], v[68:71], v[48:51]
	v_mfma_f32_16x16x32_bf16 v[60:63], v[202:205], v[84:87], v[60:63]
	s_waitcnt lgkmcnt(0)
	v_mfma_f32_16x16x32_bf16 v[60:63], v[206:209], v[80:83], v[60:63]
	v_mfma_f32_16x16x32_bf16 v[48:51], v[206:209], v[64:67], v[48:51]
	s_cbranch_vccnz .LBB0_283
	ds_bpermute_b32 v64, v143, v151
	s_lshl_b32 s6, s97, 1
	v_mov_b32_e32 v66, 0
	s_waitcnt lgkmcnt(0)
	v_add_f32_e32 v64, v151, v64
	ds_bpermute_b32 v65, v144, v64
	s_waitcnt lgkmcnt(0)
	v_add_f32_e32 v65, v64, v65
	v_mov_b32_e32 v64, 0
	v_cmp_lt_f32_e32 vcc, 0, v65
	s_and_saveexec_b64 s[4:5], vcc
	s_cbranch_execz .LBB0_280
	s_cmp_eq_u32 s6, 1
	s_cselect_b64 vcc, -1, 0
	s_cmp_eq_u32 s6, 2
	v_cndmask_b32_e32 v66, v126, v7, vcc
	s_cselect_b64 vcc, -1, 0
	s_cmp_eq_u32 s6, 3
	v_cndmask_b32_e32 v66, v66, v2, vcc
	s_cselect_b64 vcc, -1, 0
	s_cmp_eq_u32 s6, 4
	v_cndmask_b32_e32 v66, v66, v3, vcc
	s_cselect_b64 vcc, -1, 0
	s_cmp_eq_u32 s6, 5
	v_cndmask_b32_e32 v66, v66, v4, vcc
	s_cselect_b64 vcc, -1, 0
	v_cndmask_b32_e32 v66, v66, v5, vcc
	v_div_scale_f32 v67, s[42:43], v65, v65, v66
	v_rcp_f32_e32 v68, v67
	s_nop 0
	v_fma_f32 v69, -v67, v68, 1.0
	v_fmac_f32_e32 v68, v69, v68
	v_div_scale_f32 v69, vcc, v66, v65, v66
	v_mul_f32_e32 v70, v69, v68
	v_fma_f32 v71, -v67, v70, v69
	v_fmac_f32_e32 v70, v71, v68
	v_fma_f32 v67, -v67, v70, v69
	v_div_fmas_f32 v67, v67, v68, v70
	v_div_fixup_f32 v66, v67, v65, v66
